# accumulator zeroing via v_mov_b64 (half the VALU instrs at tile headers)
# speedup vs baseline: 1.0121x; 1.0121x over previous
.LBB0_253:
	s_add_i32 s54, s54, 1
	s_mov_b64 s[2:3], s[10:11]
	s_mov_b32 s60, s6
	s_mov_b32 s10, s6
	s_lshl_b32 s6, s54, 5
	s_add_i32 s6, s6, s63
	s_cmp_lt_i32 s6, 64
	s_cselect_b64 s[44:45], -1, 0
	s_ashr_i32 s6, s6, 2
	s_mov_b64 s[0:1], s[8:9]
	s_and_b64 s[8:9], s[44:45], exec
	s_cselect_b32 s8, s35, s35
	s_cselect_b32 s10, s6, s10
	s_ashr_i32 s9, s8, 31
	s_lshl_b64 s[8:9], s[8:9], 20
	s_add_u32 s8, s21, s8
	s_addc_u32 s9, s23, s9
	s_and_b64 s[46:47], s[44:45], exec
	s_cselect_b32 s61, s9, s1
	s_cselect_b32 s72, s8, s0
	s_ashr_i32 s11, s10, 31
	s_lshl_b64 s[10:11], s[10:11], 20
	s_add_u32 s10, s70, s10
	s_addc_u32 s11, s71, s11
	s_and_b64 s[46:47], s[44:45], exec
	s_cselect_b32 s73, s11, s3
	s_cselect_b32 s74, s10, s2
	s_add_u32 s0, s0, 0x80080
	s_addc_u32 s1, s1, 0
	s_add_u32 s75, s2, 0x100
	s_addc_u32 s76, s3, 0
	s_mov_b32 s77, -2
	s_waitcnt lgkmcnt(0)
	v_mov_b64_e32 v[0:1], 0
	v_mov_b64_e32 v[2:3], 0
	v_mov_b64_e32 v[4:5], 0
	v_mov_b64_e32 v[6:7], 0
	v_mov_b64_e32 v[16:17], 0
	v_mov_b64_e32 v[18:19], 0
	v_mov_b64_e32 v[20:21], 0
	v_mov_b64_e32 v[22:23], 0
	v_mov_b64_e32 v[32:33], 0
	v_mov_b64_e32 v[34:35], 0
	v_mov_b64_e32 v[36:37], 0
	v_mov_b64_e32 v[38:39], 0
	v_mov_b64_e32 v[64:65], 0
	v_mov_b64_e32 v[66:67], 0
	v_mov_b64_e32 v[68:69], 0
	v_mov_b64_e32 v[70:71], 0
	v_mov_b64_e32 v[8:9], 0
	v_mov_b64_e32 v[10:11], 0
	v_mov_b64_e32 v[12:13], 0
	v_mov_b64_e32 v[14:15], 0
	v_mov_b64_e32 v[24:25], 0
	v_mov_b64_e32 v[26:27], 0
	v_mov_b64_e32 v[28:29], 0
	v_mov_b64_e32 v[30:31], 0
	v_mov_b64_e32 v[56:57], 0
	v_mov_b64_e32 v[58:59], 0
	v_mov_b64_e32 v[60:61], 0
	v_mov_b64_e32 v[62:63], 0
	v_mov_b64_e32 v[72:73], 0
	v_mov_b64_e32 v[74:75], 0
	v_mov_b64_e32 v[76:77], 0
	v_mov_b64_e32 v[78:79], 0
	v_mov_b64_e32 v[80:81], 0
	v_mov_b64_e32 v[82:83], 0
	v_mov_b64_e32 v[84:85], 0
	v_mov_b64_e32 v[86:87], 0
	v_mov_b64_e32 v[96:97], 0
	v_mov_b64_e32 v[98:99], 0
	v_mov_b64_e32 v[100:101], 0
	v_mov_b64_e32 v[102:103], 0
	v_mov_b64_e32 v[112:113], 0
	v_mov_b64_e32 v[114:115], 0
	v_mov_b64_e32 v[116:117], 0
	v_mov_b64_e32 v[118:119], 0
	v_mov_b64_e32 v[128:129], 0
	v_mov_b64_e32 v[130:131], 0
	v_mov_b64_e32 v[132:133], 0
	v_mov_b64_e32 v[134:135], 0
	v_mov_b64_e32 v[88:89], 0
	v_mov_b64_e32 v[90:91], 0
	v_mov_b64_e32 v[92:93], 0
	v_mov_b64_e32 v[94:95], 0
	v_mov_b64_e32 v[104:105], 0
	v_mov_b64_e32 v[106:107], 0
	v_mov_b64_e32 v[108:109], 0
	v_mov_b64_e32 v[110:111], 0
	v_mov_b64_e32 v[120:121], 0
	v_mov_b64_e32 v[122:123], 0
	v_mov_b64_e32 v[124:125], 0
	v_mov_b64_e32 v[126:127], 0
	v_mov_b64_e32 v[136:137], 0
	v_mov_b64_e32 v[138:139], 0
	v_mov_b64_e32 v[140:141], 0
	v_mov_b64_e32 v[142:143], 0
	s_lshr_b32 s101, s88, 2
	s_cmp_lg_u32 s101, 0
	s_cbranch_scc1 .Lprio_skip1
	s_setprio 1

.LBB0_515:
	v_mov_b64_e32 v[84:85], 0
	v_mov_b64_e32 v[86:87], 0
	s_and_b64 vcc, exec, s[72:73]
	s_cbranch_vccz .LBB0_521
.LBB0_516:
	v_mov_b64_e32 v[88:89], 0
	v_mov_b64_e32 v[90:91], 0
	s_branch .LBB0_522

.LBB0_519:
	v_mov_b64_e32 v[76:77], 0
	v_mov_b64_e32 v[78:79], 0
	s_and_b64 vcc, exec, s[70:71]
	s_cbranch_vccnz .LBB0_515

.LBB0_784:
	s_add_i32 s53, s53, 1
	s_mov_b64 s[38:39], s[10:11]
	s_mov_b32 s68, s4
	s_mov_b32 s10, s4
	s_lshl_b32 s4, s53, 5
	s_add_i32 s4, s4, s19
	s_cmp_lt_i32 s4, 32
	s_cselect_b64 s[34:35], -1, 0
	s_ashr_i32 s4, s4, 2
	s_mov_b64 s[36:37], s[8:9]
	s_and_b64 s[8:9], s[34:35], exec
	s_cselect_b32 s8, s42, s42
	s_cselect_b32 s10, s4, s10
	s_ashr_i32 s9, s8, 31
	s_lshl_b64 s[8:9], s[8:9], 20
	s_add_u32 s8, s43, s8
	s_addc_u32 s9, s44, s9
	s_and_b64 s[40:41], s[34:35], exec
	s_cselect_b32 s69, s9, s37
	s_cselect_b32 s70, s8, s36
	s_ashr_i32 s11, s10, 31
	s_lshl_b64 s[10:11], s[10:11], 20
	s_add_u32 s10, s45, s10
	s_addc_u32 s11, s46, s11
	s_and_b64 s[40:41], s[34:35], exec
	s_cselect_b32 s71, s11, s39
	s_cselect_b32 s72, s10, s38
	s_add_u32 s36, s36, 0x80080
	s_addc_u32 s37, s37, 0
	s_add_u32 s73, s38, 0x100
	s_addc_u32 s74, s39, 0
	s_mov_b32 s75, -2
	v_mov_b64_e32 v[0:1], 0
	v_mov_b64_e32 v[2:3], 0
	v_mov_b64_e32 v[4:5], 0
	v_mov_b64_e32 v[6:7], 0
	v_mov_b64_e32 v[12:13], 0
	v_mov_b64_e32 v[14:15], 0
	v_mov_b64_e32 v[20:21], 0
	v_mov_b64_e32 v[22:23], 0
	v_mov_b64_e32 v[28:29], 0
	v_mov_b64_e32 v[30:31], 0
	v_mov_b64_e32 v[36:37], 0
	v_mov_b64_e32 v[38:39], 0
	v_mov_b64_e32 v[44:45], 0
	v_mov_b64_e32 v[46:47], 0
	v_mov_b64_e32 v[52:53], 0
	v_mov_b64_e32 v[54:55], 0
	v_mov_b64_e32 v[8:9], 0
	v_mov_b64_e32 v[10:11], 0
	v_mov_b64_e32 v[16:17], 0
	v_mov_b64_e32 v[18:19], 0
	v_mov_b64_e32 v[24:25], 0
	v_mov_b64_e32 v[26:27], 0
	v_mov_b64_e32 v[32:33], 0
	v_mov_b64_e32 v[34:35], 0
	v_mov_b64_e32 v[40:41], 0
	v_mov_b64_e32 v[42:43], 0
	v_mov_b64_e32 v[48:49], 0
	v_mov_b64_e32 v[50:51], 0
	v_mov_b64_e32 v[56:57], 0
	v_mov_b64_e32 v[58:59], 0
	v_mov_b64_e32 v[60:61], 0
	v_mov_b64_e32 v[62:63], 0
	v_mov_b64_e32 v[64:65], 0
	v_mov_b64_e32 v[66:67], 0
	v_mov_b64_e32 v[68:69], 0
	v_mov_b64_e32 v[70:71], 0
	v_mov_b64_e32 v[76:77], 0
	v_mov_b64_e32 v[78:79], 0
	v_mov_b64_e32 v[84:85], 0
	v_mov_b64_e32 v[86:87], 0
	v_mov_b64_e32 v[92:93], 0
	v_mov_b64_e32 v[94:95], 0
	v_mov_b64_e32 v[100:101], 0
	v_mov_b64_e32 v[102:103], 0
	v_mov_b64_e32 v[108:109], 0
	v_mov_b64_e32 v[110:111], 0
	v_mov_b64_e32 v[116:117], 0
	v_mov_b64_e32 v[118:119], 0
	v_mov_b64_e32 v[72:73], 0
	v_mov_b64_e32 v[74:75], 0
	v_mov_b64_e32 v[80:81], 0
	v_mov_b64_e32 v[82:83], 0
	v_mov_b64_e32 v[88:89], 0
	v_mov_b64_e32 v[90:91], 0
	v_mov_b64_e32 v[96:97], 0
	v_mov_b64_e32 v[98:99], 0
	v_mov_b64_e32 v[104:105], 0
	v_mov_b64_e32 v[106:107], 0
	v_mov_b64_e32 v[112:113], 0
	v_mov_b64_e32 v[114:115], 0
	v_mov_b64_e32 v[120:121], 0
	v_mov_b64_e32 v[122:123], 0
	v_mov_b64_e32 v[124:125], 0
	v_mov_b64_e32 v[126:127], 0
	s_lshr_b32 s101, s88, 2
	s_cmp_lg_u32 s101, 0
	s_cbranch_scc1 .Lprio_skip5
	s_setprio 1

.LBB0_1083:
	s_add_i32 s52, s52, 1
	s_mov_b64 s[36:37], s[10:11]
	s_mov_b32 s67, s4
	s_mov_b32 s10, s4
	s_lshl_b32 s4, s52, 5
	s_add_i32 s4, s4, s40
	s_cmpk_lt_i32 s4, 0x80
	s_cselect_b64 s[34:35], -1, 0
	s_ashr_i32 s4, s4, 2
	s_mov_b64 s[0:1], s[8:9]
	s_and_b64 s[8:9], s[34:35], exec
	s_cselect_b32 s8, s41, s41
	s_cselect_b32 s10, s4, s10
	s_ashr_i32 s9, s8, 31
	s_lshl_b64 s[8:9], s[8:9], 20
	s_add_u32 s8, s42, s8
	s_addc_u32 s9, s43, s9
	s_and_b64 s[38:39], s[34:35], exec
	s_cselect_b32 s68, s9, s1
	s_cselect_b32 s69, s8, s0
	s_ashr_i32 s11, s10, 31
	s_lshl_b64 s[10:11], s[10:11], 20
	s_add_u32 s10, s44, s10
	s_addc_u32 s11, s45, s11
	s_and_b64 s[38:39], s[34:35], exec
	s_cselect_b32 s70, s11, s37
	s_cselect_b32 s71, s10, s36
	s_add_u32 s0, s0, 0x80080
	s_addc_u32 s1, s1, 0
	s_add_u32 s72, s36, 0x100
	s_addc_u32 s73, s37, 0
	s_mov_b32 s74, -2
	v_mov_b64_e32 v[0:1], 0
	v_mov_b64_e32 v[2:3], 0
	v_mov_b64_e32 v[4:5], 0
	v_mov_b64_e32 v[6:7], 0
	v_mov_b64_e32 v[16:17], 0
	v_mov_b64_e32 v[18:19], 0
	v_mov_b64_e32 v[20:21], 0
	v_mov_b64_e32 v[22:23], 0
	v_mov_b64_e32 v[32:33], 0
	v_mov_b64_e32 v[34:35], 0
	v_mov_b64_e32 v[36:37], 0
	v_mov_b64_e32 v[38:39], 0
	v_mov_b64_e32 v[48:49], 0
	v_mov_b64_e32 v[50:51], 0
	v_mov_b64_e32 v[52:53], 0
	v_mov_b64_e32 v[54:55], 0
	v_mov_b64_e32 v[8:9], 0
	v_mov_b64_e32 v[10:11], 0
	v_mov_b64_e32 v[12:13], 0
	v_mov_b64_e32 v[14:15], 0
	v_mov_b64_e32 v[24:25], 0
	v_mov_b64_e32 v[26:27], 0
	v_mov_b64_e32 v[28:29], 0
	v_mov_b64_e32 v[30:31], 0
	v_mov_b64_e32 v[40:41], 0
	v_mov_b64_e32 v[42:43], 0
	v_mov_b64_e32 v[44:45], 0
	v_mov_b64_e32 v[46:47], 0
	v_mov_b64_e32 v[56:57], 0
	v_mov_b64_e32 v[58:59], 0
	v_mov_b64_e32 v[60:61], 0
	v_mov_b64_e32 v[62:63], 0
	v_mov_b64_e32 v[64:65], 0
	v_mov_b64_e32 v[66:67], 0
	v_mov_b64_e32 v[68:69], 0
	v_mov_b64_e32 v[70:71], 0
	v_mov_b64_e32 v[80:81], 0
	v_mov_b64_e32 v[82:83], 0
	v_mov_b64_e32 v[84:85], 0
	v_mov_b64_e32 v[86:87], 0
	v_mov_b64_e32 v[96:97], 0
	v_mov_b64_e32 v[98:99], 0
	v_mov_b64_e32 v[100:101], 0
	v_mov_b64_e32 v[102:103], 0
	v_mov_b64_e32 v[112:113], 0
	v_mov_b64_e32 v[114:115], 0
	v_mov_b64_e32 v[116:117], 0
	v_mov_b64_e32 v[118:119], 0
	v_mov_b64_e32 v[72:73], 0
	v_mov_b64_e32 v[74:75], 0
	v_mov_b64_e32 v[76:77], 0
	v_mov_b64_e32 v[78:79], 0
	v_mov_b64_e32 v[88:89], 0
	v_mov_b64_e32 v[90:91], 0
	v_mov_b64_e32 v[92:93], 0
	v_mov_b64_e32 v[94:95], 0
	v_mov_b64_e32 v[104:105], 0
	v_mov_b64_e32 v[106:107], 0
	v_mov_b64_e32 v[108:109], 0
	v_mov_b64_e32 v[110:111], 0
	v_mov_b64_e32 v[120:121], 0
	v_mov_b64_e32 v[122:123], 0
	v_mov_b64_e32 v[124:125], 0
	v_mov_b64_e32 v[126:127], 0
	s_lshr_b32 s101, s88, 2
	s_cmp_lg_u32 s101, 0
	s_cbranch_scc1 .Lprio_skip7
	s_setprio 1

.LBB0_1323:
	s_add_i32 s50, s50, 1
	s_mov_b64 s[34:35], s[0:1]
	s_lshl_b32 s0, s50, 5
	s_add_i32 s0, s0, s38
	s_cmp_lt_i32 s0, 32
	s_mov_b64 s[30:31], s[6:7]
	s_mov_b32 s65, s4
	s_mov_b32 s6, s4
	s_cselect_b64 s[28:29], -1, 0
	s_ashr_i32 s4, s0, 2
	s_and_b64 s[0:1], s[28:29], exec
	s_cselect_b32 s0, s4, s6
	s_cselect_b32 s6, s39, s39
	s_ashr_i32 s7, s6, 31
	s_lshl_b64 s[6:7], s[6:7], 20
	s_add_u32 s6, s40, s6
	s_addc_u32 s7, s41, s7
	s_and_b64 s[36:37], s[28:29], exec
	s_cselect_b32 s66, s7, s31
	s_cselect_b32 s67, s6, s30
	s_ashr_i32 s1, s0, 31
	s_lshl_b64 s[0:1], s[0:1], 20
	s_add_u32 s0, s42, s0
	s_addc_u32 s1, s43, s1
	s_and_b64 s[36:37], s[28:29], exec
	s_cselect_b32 s68, s1, s35
	s_cselect_b32 s69, s0, s34
	s_add_u32 s30, s30, 0x80080
	s_addc_u32 s31, s31, 0
	s_add_u32 s70, s34, 0x100
	s_addc_u32 s71, s35, 0
	s_mov_b32 s72, -2
	v_mov_b64_e32 v[0:1], 0
	v_mov_b64_e32 v[2:3], 0
	v_mov_b64_e32 v[4:5], 0
	v_mov_b64_e32 v[6:7], 0
	v_mov_b64_e32 v[12:13], 0
	v_mov_b64_e32 v[14:15], 0
	v_mov_b64_e32 v[20:21], 0
	v_mov_b64_e32 v[22:23], 0
	v_mov_b64_e32 v[28:29], 0
	v_mov_b64_e32 v[30:31], 0
	v_mov_b64_e32 v[36:37], 0
	v_mov_b64_e32 v[38:39], 0
	v_mov_b64_e32 v[44:45], 0
	v_mov_b64_e32 v[46:47], 0
	v_mov_b64_e32 v[52:53], 0
	v_mov_b64_e32 v[54:55], 0
	v_mov_b64_e32 v[8:9], 0
	v_mov_b64_e32 v[10:11], 0
	v_mov_b64_e32 v[16:17], 0
	v_mov_b64_e32 v[18:19], 0
	v_mov_b64_e32 v[24:25], 0
	v_mov_b64_e32 v[26:27], 0
	v_mov_b64_e32 v[32:33], 0
	v_mov_b64_e32 v[34:35], 0
	v_mov_b64_e32 v[40:41], 0
	v_mov_b64_e32 v[42:43], 0
	v_mov_b64_e32 v[48:49], 0
	v_mov_b64_e32 v[50:51], 0
	v_mov_b64_e32 v[56:57], 0
	v_mov_b64_e32 v[58:59], 0
	v_mov_b64_e32 v[60:61], 0
	v_mov_b64_e32 v[62:63], 0
	v_mov_b64_e32 v[64:65], 0
	v_mov_b64_e32 v[66:67], 0
	v_mov_b64_e32 v[68:69], 0
	v_mov_b64_e32 v[70:71], 0
	v_mov_b64_e32 v[76:77], 0
	v_mov_b64_e32 v[78:79], 0
	v_mov_b64_e32 v[84:85], 0
	v_mov_b64_e32 v[86:87], 0
	v_mov_b64_e32 v[92:93], 0
	v_mov_b64_e32 v[94:95], 0
	v_mov_b64_e32 v[100:101], 0
	v_mov_b64_e32 v[102:103], 0
	v_mov_b64_e32 v[108:109], 0
	v_mov_b64_e32 v[110:111], 0
	v_mov_b64_e32 v[116:117], 0
	v_mov_b64_e32 v[118:119], 0
	v_mov_b64_e32 v[72:73], 0
	v_mov_b64_e32 v[74:75], 0
	v_mov_b64_e32 v[80:81], 0
	v_mov_b64_e32 v[82:83], 0
	v_mov_b64_e32 v[88:89], 0
	v_mov_b64_e32 v[90:91], 0
	v_mov_b64_e32 v[96:97], 0
	v_mov_b64_e32 v[98:99], 0
	v_mov_b64_e32 v[104:105], 0
	v_mov_b64_e32 v[106:107], 0
	v_mov_b64_e32 v[112:113], 0
	v_mov_b64_e32 v[114:115], 0
	v_mov_b64_e32 v[120:121], 0
	v_mov_b64_e32 v[122:123], 0
	v_mov_b64_e32 v[124:125], 0
	v_mov_b64_e32 v[126:127], 0
	s_lshr_b32 s101, s88, 2
	s_cmp_lg_u32 s101, 0
	s_cbranch_scc1 .Lprio_skip9
	s_setprio 1

.LBB0_1954:
	s_add_i32 s52, s52, 1
	s_mov_b64 s[36:37], s[10:11]
	s_mov_b32 s67, s6
	s_mov_b32 s10, s6
	s_lshl_b32 s6, s52, 5
	s_add_i32 s6, s6, s40
	s_cmpk_lt_i32 s6, 0x80
	s_cselect_b64 s[34:35], -1, 0
	s_ashr_i32 s6, s6, 2
	s_mov_b64 s[0:1], s[8:9]
	s_and_b64 s[8:9], s[34:35], exec
	s_cselect_b32 s8, s41, s41
	s_cselect_b32 s10, s6, s10
	s_ashr_i32 s9, s8, 31
	s_lshl_b64 s[8:9], s[8:9], 20
	s_add_u32 s8, s42, s8
	s_addc_u32 s9, s43, s9
	s_and_b64 s[38:39], s[34:35], exec
	s_cselect_b32 s68, s9, s1
	s_cselect_b32 s69, s8, s0
	s_ashr_i32 s11, s10, 31
	s_lshl_b64 s[10:11], s[10:11], 20
	s_add_u32 s10, s44, s10
	s_addc_u32 s11, s45, s11
	s_and_b64 s[38:39], s[34:35], exec
	s_cselect_b32 s70, s11, s37
	s_cselect_b32 s71, s10, s36
	s_add_u32 s0, s0, 0x80080
	s_addc_u32 s1, s1, 0
	s_add_u32 s72, s36, 0x100
	s_addc_u32 s73, s37, 0
	s_mov_b32 s74, -2
	v_mov_b64_e32 v[0:1], 0
	v_mov_b64_e32 v[2:3], 0
	v_mov_b64_e32 v[4:5], 0
	v_mov_b64_e32 v[6:7], 0
	v_mov_b64_e32 v[16:17], 0
	v_mov_b64_e32 v[18:19], 0
	v_mov_b64_e32 v[20:21], 0
	v_mov_b64_e32 v[22:23], 0
	v_mov_b64_e32 v[32:33], 0
	v_mov_b64_e32 v[34:35], 0
	v_mov_b64_e32 v[36:37], 0
	v_mov_b64_e32 v[38:39], 0
	v_mov_b64_e32 v[48:49], 0
	v_mov_b64_e32 v[50:51], 0
	v_mov_b64_e32 v[52:53], 0
	v_mov_b64_e32 v[54:55], 0
	v_mov_b64_e32 v[8:9], 0
	v_mov_b64_e32 v[10:11], 0
	v_mov_b64_e32 v[12:13], 0
	v_mov_b64_e32 v[14:15], 0
	v_mov_b64_e32 v[24:25], 0
	v_mov_b64_e32 v[26:27], 0
	v_mov_b64_e32 v[28:29], 0
	v_mov_b64_e32 v[30:31], 0
	v_mov_b64_e32 v[40:41], 0
	v_mov_b64_e32 v[42:43], 0
	v_mov_b64_e32 v[44:45], 0
	v_mov_b64_e32 v[46:47], 0
	v_mov_b64_e32 v[56:57], 0
	v_mov_b64_e32 v[58:59], 0
	v_mov_b64_e32 v[60:61], 0
	v_mov_b64_e32 v[62:63], 0
	v_mov_b64_e32 v[64:65], 0
	v_mov_b64_e32 v[66:67], 0
	v_mov_b64_e32 v[68:69], 0
	v_mov_b64_e32 v[70:71], 0
	v_mov_b64_e32 v[80:81], 0
	v_mov_b64_e32 v[82:83], 0
	v_mov_b64_e32 v[84:85], 0
	v_mov_b64_e32 v[86:87], 0
	v_mov_b64_e32 v[96:97], 0
	v_mov_b64_e32 v[98:99], 0
	v_mov_b64_e32 v[100:101], 0
	v_mov_b64_e32 v[102:103], 0
	v_mov_b64_e32 v[112:113], 0
	v_mov_b64_e32 v[114:115], 0
	v_mov_b64_e32 v[116:117], 0
	v_mov_b64_e32 v[118:119], 0
	v_mov_b64_e32 v[72:73], 0
	v_mov_b64_e32 v[74:75], 0
	v_mov_b64_e32 v[76:77], 0
	v_mov_b64_e32 v[78:79], 0
	v_mov_b64_e32 v[88:89], 0
	v_mov_b64_e32 v[90:91], 0
	v_mov_b64_e32 v[92:93], 0
	v_mov_b64_e32 v[94:95], 0
	v_mov_b64_e32 v[104:105], 0
	v_mov_b64_e32 v[106:107], 0
	v_mov_b64_e32 v[108:109], 0
	v_mov_b64_e32 v[110:111], 0
	v_mov_b64_e32 v[120:121], 0
	v_mov_b64_e32 v[122:123], 0
	v_mov_b64_e32 v[124:125], 0
	v_mov_b64_e32 v[126:127], 0
	s_lshr_b32 s101, s88, 2
	s_cmp_lg_u32 s101, 0
	s_cbranch_scc1 .Lprio_skip13
	s_setprio 1
